# RWKV-7 producer stage B: second-tile MFMA fragments preloaded under the gate exp/rcp math so the second MFMA chain issues without LDS waits
# speedup vs baseline: 1.0025x; 1.0004x over previous
.LBB0_184:
	s_andn2_b64 vcc, exec, s[46:47]
	s_cbranch_vccnz .LBB0_186
	ds_read_b128 v[222:225], v102
	ds_read_b128 v[30:33], v93
	ds_read_b128 v[226:229], v102 offset:64
	ds_read_b128 v[34:37], v93 offset:64
	ds_read_b128 v[230:233], v103
	ds_read_b128 v[42:45], v94
	ds_read_b128 v[126:129], v103 offset:64
	ds_read_b128 v[46:49], v94 offset:64
	s_waitcnt lgkmcnt(6)
	v_mfma_f32_16x16x32_bf16 v[38:41], v[222:225], v[30:33], 0
	s_waitcnt lgkmcnt(4)
	v_mfma_f32_16x16x32_bf16 v[38:41], v[226:229], v[34:37], v[38:41]
	s_waitcnt lgkmcnt(2)
	v_mfma_f32_16x16x32_bf16 v[122:125], v[230:233], v[42:45], 0
	s_nop 7
	s_waitcnt vmcnt(5)
	s_nop 0
	v_add_f32_e32 v38, v113, v38
	v_add_f32_e32 v39, v113, v39
	v_mul_f32_e32 v38, 0xbfb8aa3b, v38
	v_mul_f32_e32 v39, 0xbfb8aa3b, v39
	v_exp_f32_e32 v38, v38
	v_exp_f32_e32 v39, v39
	s_waitcnt lgkmcnt(0)
	v_mfma_f32_16x16x32_bf16 v[122:125], v[126:129], v[46:49], v[122:125]
	ds_read2st64_b32 v[126:127], v65 offset0:64 offset1:65
	ds_read_b128 v[234:237], v105
	ds_read_b128 v[238:241], v106 offset:64
	ds_read_b128 v[222:225], v107
	ds_read_b128 v[226:229], v108 offset:64
	v_add_f32_e32 v38, 1.0, v38
	v_add_f32_e32 v39, 1.0, v39
	v_rcp_f32_e32 v38, v38
	v_rcp_f32_e32 v39, v39
	s_waitcnt vmcnt(4)
	s_nop 1
	v_add_f32_e32 v122, v114, v122
	v_add_f32_e32 v123, v114, v123
	v_mul_f32_e32 v122, 0xbfb8aa3b, v122
	v_mul_f32_e32 v123, 0xbfb8aa3b, v123
	v_exp_f32_e32 v122, v122
	v_exp_f32_e32 v123, v123
	v_mul_f32_e32 v38, 0xbf1b4598, v38
	v_mul_f32_e32 v39, 0xbf1b4598, v39
	v_mul_f32_e32 v38, 0x3fb8aa3b, v38
	v_mul_f32_e32 v39, 0x3fb8aa3b, v39
	v_add_f32_e32 v122, 1.0, v122
	v_exp_f32_e32 v38, v38
	v_add_f32_e32 v123, 1.0, v123
	v_exp_f32_e32 v39, v39
	v_rcp_f32_e32 v122, v122
	v_rcp_f32_e32 v123, v123
	s_waitcnt vmcnt(3) lgkmcnt(4)
	v_mul_f32_e32 v128, v115, v126
	ds_write2st64_b32 v65, v38, v39 offset0:32 offset1:33
	v_mul_f32_e32 v38, v115, v127
	v_add_f32_e32 v129, -1.0, v122
	ds_write2st64_b32 v65, v128, v38 offset0:96 offset1:97
	v_add_f32_e32 v38, -1.0, v123
	s_waitcnt vmcnt(2)
	v_fma_f32 v129, v116, v129, 1.0
	v_fma_f32 v38, v116, v38, 1.0
	v_mul_f32_e32 v126, v126, v129
	v_mul_f32_e32 v38, v127, v38
	ds_write2st64_b32 v65, v126, v38 offset0:64 offset1:65
	ds_write2st64_b32 v65, v122, v123 offset0:128 offset1:129
	v_add_f32_e32 v38, v114, v124
	v_mul_f32_e32 v38, 0xbfb8aa3b, v38
	v_exp_f32_e32 v38, v38
	v_add_f32_e32 v40, v113, v40
	v_add_f32_e32 v41, v113, v41
	v_mul_f32_e32 v40, 0xbfb8aa3b, v40
	v_add_f32_e32 v38, 1.0, v38
	v_rcp_f32_e32 v122, v38
	v_mul_f32_e32 v41, 0xbfb8aa3b, v41
	ds_read2st64_b32 v[38:39], v65 offset0:66 offset1:67
	v_exp_f32_e32 v40, v40
	v_exp_f32_e32 v41, v41
	v_add_f32_e32 v124, -1.0, v122
	v_fma_f32 v124, v116, v124, 1.0
	v_add_f32_e32 v40, 1.0, v40
	v_add_f32_e32 v41, 1.0, v41
	v_rcp_f32_e32 v40, v40
	s_waitcnt lgkmcnt(0)
	v_mul_f32_e32 v123, v115, v38
	v_mul_f32_e32 v38, v124, v38
	v_add_f32_e32 v124, v114, v125
	v_rcp_f32_e32 v41, v41
	v_mul_f32_e32 v124, 0xbfb8aa3b, v124
	v_exp_f32_e32 v124, v124
	v_mul_f32_e32 v40, 0xbf1b4598, v40
	v_mul_f32_e32 v41, 0xbf1b4598, v41
	v_mul_f32_e32 v40, 0x3fb8aa3b, v40
	v_mul_f32_e32 v41, 0x3fb8aa3b, v41
	v_exp_f32_e32 v40, v40
	v_add_f32_e32 v124, 1.0, v124
	v_exp_f32_e32 v41, v41
	v_rcp_f32_e32 v124, v124
	ds_write2st64_b32 v65, v40, v41 offset0:34 offset1:35
	v_mul_f32_e32 v40, v115, v39
	ds_write2st64_b32 v65, v123, v40 offset0:98 offset1:99
	v_add_f32_e32 v40, -1.0, v124
	v_fma_f32 v40, v116, v40, 1.0
	v_mul_f32_e32 v39, v40, v39
	ds_write2st64_b32 v65, v38, v39 offset0:66 offset1:67
	ds_write2st64_b32 v65, v122, v124 offset0:130 offset1:131
	v_mfma_f32_16x16x32_bf16 v[30:33], v[234:237], v[30:33], 0
	v_mfma_f32_16x16x32_bf16 v[30:33], v[238:241], v[34:37], v[30:33]
	s_nop 3
	s_nop 5
	v_add_f32_e32 v30, v113, v30
	v_mfma_f32_16x16x32_bf16 v[34:37], v[222:225], v[42:45], 0
	v_add_f32_e32 v31, v113, v31
	v_mul_f32_e32 v30, 0xbfb8aa3b, v30
	v_mul_f32_e32 v31, 0xbfb8aa3b, v31
	v_exp_f32_e32 v30, v30
	v_exp_f32_e32 v31, v31
	v_mfma_f32_16x16x32_bf16 v[34:37], v[226:229], v[46:49], v[34:37]
	ds_read2st64_b32 v[38:39], v65 offset0:80 offset1:81
	v_add_f32_e32 v30, 1.0, v30
	v_add_f32_e32 v31, 1.0, v31
	v_rcp_f32_e32 v30, v30
	v_rcp_f32_e32 v31, v31
	s_nop 2
	v_add_f32_e32 v34, v114, v34
	v_add_f32_e32 v35, v114, v35
	v_mul_f32_e32 v34, 0xbfb8aa3b, v34
	v_mul_f32_e32 v35, 0xbfb8aa3b, v35
	v_exp_f32_e32 v34, v34
	v_exp_f32_e32 v35, v35
	v_mul_f32_e32 v30, 0xbf1b4598, v30
	v_mul_f32_e32 v31, 0xbf1b4598, v31
	v_mul_f32_e32 v30, 0x3fb8aa3b, v30
	v_mul_f32_e32 v31, 0x3fb8aa3b, v31
	v_add_f32_e32 v34, 1.0, v34
	v_exp_f32_e32 v30, v30
	v_add_f32_e32 v35, 1.0, v35
	v_exp_f32_e32 v31, v31
	v_rcp_f32_e32 v34, v34
	v_rcp_f32_e32 v35, v35
	s_waitcnt lgkmcnt(0)
	v_mul_f32_e32 v40, v115, v38
	ds_write2st64_b32 v65, v30, v31 offset0:48 offset1:49
	v_mul_f32_e32 v30, v115, v39
	v_add_f32_e32 v41, -1.0, v34
	ds_write2st64_b32 v65, v40, v30 offset0:112 offset1:113
	v_add_f32_e32 v30, -1.0, v35
	v_fma_f32 v41, v116, v41, 1.0
	v_fma_f32 v30, v116, v30, 1.0
	v_mul_f32_e32 v38, v38, v41
	v_mul_f32_e32 v30, v39, v30
	ds_write2st64_b32 v65, v38, v30 offset0:80 offset1:81
	ds_write2st64_b32 v65, v34, v35 offset0:144 offset1:145
	v_add_f32_e32 v30, v114, v36
	v_mul_f32_e32 v30, 0xbfb8aa3b, v30
	v_exp_f32_e32 v30, v30
	v_add_f32_e32 v34, v113, v32
	v_add_f32_e32 v33, v113, v33
	v_mul_f32_e32 v34, 0xbfb8aa3b, v34
	v_add_f32_e32 v30, 1.0, v30
	v_rcp_f32_e32 v32, v30
	v_mul_f32_e32 v33, 0xbfb8aa3b, v33
	ds_read2st64_b32 v[30:31], v65 offset0:82 offset1:83
	v_exp_f32_e32 v34, v34
	v_exp_f32_e32 v33, v33
	v_add_f32_e32 v36, -1.0, v32
	v_fma_f32 v36, v116, v36, 1.0
	v_add_f32_e32 v34, 1.0, v34
	v_add_f32_e32 v33, 1.0, v33
	v_rcp_f32_e32 v34, v34
	s_waitcnt lgkmcnt(0)
	v_mul_f32_e32 v35, v115, v30
	v_mul_f32_e32 v30, v36, v30
	v_add_f32_e32 v36, v114, v37
	v_rcp_f32_e32 v33, v33
	v_mul_f32_e32 v36, 0xbfb8aa3b, v36
	v_exp_f32_e32 v36, v36
	v_mul_f32_e32 v34, 0xbf1b4598, v34
	v_mul_f32_e32 v33, 0xbf1b4598, v33
	v_mul_f32_e32 v34, 0x3fb8aa3b, v34
	v_mul_f32_e32 v33, 0x3fb8aa3b, v33
	v_exp_f32_e32 v34, v34
	v_add_f32_e32 v36, 1.0, v36
	v_exp_f32_e32 v33, v33
	v_rcp_f32_e32 v36, v36
	ds_write2st64_b32 v65, v34, v33 offset0:50 offset1:51
	v_mul_f32_e32 v33, v115, v31
	ds_write2st64_b32 v65, v35, v33 offset0:114 offset1:115
	v_add_f32_e32 v33, -1.0, v36
	v_fma_f32 v33, v116, v33, 1.0
	v_mul_f32_e32 v31, v33, v31
	ds_write2st64_b32 v65, v30, v31 offset0:82 offset1:83
	ds_write2st64_b32 v65, v32, v36 offset0:146 offset1:147
